# v39 + rescale-diamond not-taken v_mov removed at 8 more sites (22 of 24), exact
# speedup vs baseline: 1.0059x; 1.0050x over previous
; #define TIDX opaque_tid()
; __device__ __forceinline__ unsigned pk2(float lo, float hi) { const f32x2v v = {lo, hi}; const bf16x2v r = __builtin_convertvector(v, bf16x2v); return __builtin_bit_cast(unsigned, r); }
; __device__ __forceinline__ void kv_lwrite(const KVRegs& r, char* lds, int buf) {
;   const int tid = TIDX, row = tid >> 3, cq = tid & 7;
;   char* kt = lds + NSA_KT + buf * 8192 + row * 128;
;   *(u32x4*)(kt + ((cq ^ (row & 7)) << 4)) = r.k0;
;   bf16_t* vt = (bf16_t*)(lds + NSA_VT + buf * 8704) + (cq * 8) * 68 + row;
; #pragma unroll
;   for (int i = 0; i < 4; ++i) { vt[(2 * i) * 68] = (bf16_t)(r.v0[i] & 0xffffu); vt[(2 * i + 1) * 68] = (bf16_t)(r.v0[i] >> 16); }
; }
; template <int MODE>
; __device__ __forceinline__ void nsa_compute(int cur, int buf, int t, int hl, u64 mymask, const bf16x8 (&Qf)[2][2], f32x4 (&O)[4][2], float (&m)[2], float (&l)[2],
;                                             const float (&inv)[2], float* impw, char* lds) {
;     ...
;         const float me = (MODE == 2) ? (selok ? m[r] : __builtin_inff()) : m[r];
;         float ps = 0.f;
; #pragma unroll
;         for (int kk = 0; kk < 2; ++kk)
; #pragma unroll
;           for (int e = 0; e < 4; ++e) { pv[kk][e] = __builtin_amdgcn_exp2f(sv[kk][e] - me); ps += pv[kk][e]; }
;         l[r] += ps;
;       }
;       if (MODE != 0) {
;         const unsigned w0 = pk2(pv[0][0], pv[0][1]), w1 = pk2(pv[0][2], pv[0][3]), w2 = pk2(pv[1][0], pv[1][1]), w3 = pk2(pv[1][2], pv[1][3]);
;         u32x4 pw; pw.x = w0; pw.y = w1; pw.z = w2; pw.w = w3;
;         Pf[r] = __builtin_bit_cast(bf16x8, pw);
;       }
;     }
;     if (MODE != 0) {
;       bf16x8 vfr[4];
; #pragma unroll
;       for (int df = 0; df < 4; ++df) {
;         const bf16x4 va = *(const bf16x4*)(vt + (df * 16 + fr) * 68 + 32 * s2 + 4 * fq);
;         const bf16x4 vb = *(const bf16x4*)(vt + (df * 16 + fr) * 68 + 32 * s2 + 16 + 4 * fq);
;         bf16x8 vf; vf[0] = va[0]; vf[1] = va[1]; vf[2] = va[2]; vf[3] = va[3]; vf[4] = vb[0]; vf[5] = vb[1]; vf[6] = vb[2]; vf[7] = vb[3];
;         vfr[df] = vf;
;       }
;       __builtin_amdgcn_s_setprio(1);
; #pragma unroll
;       for (int df = 0; df < 4; ++df)
; #pragma unroll
;         for (int r = 0; r < 2; ++r) O[df][r] = mfma16(vfr[df], Pf[r], O[df][r]);
;       __builtin_amdgcn_s_setprio(0);
;     }
.LBB0_373:
	v_sub_f32_e32 v91, v113, v193
	v_exp_f32_e32 v113, v91
	v_sub_f32_e32 v91, v112, v193
	v_exp_f32_e32 v112, v91
	v_sub_f32_e32 v91, v101, v193
	v_cvt_pk_bf16_f32 v124, v119, v114
	v_exp_f32_e32 v114, v91
	v_sub_f32_e32 v91, v100, v193
	v_cvt_pk_bf16_f32 v122, v115, v117
	v_exp_f32_e32 v115, v91
	v_sub_f32_e32 v91, v103, v193
	v_cvt_pk_bf16_f32 v123, v118, v116
	v_exp_f32_e32 v116, v91
	v_sub_f32_e32 v91, v102, v193
	ds_read2_b64 v[100:103], v137 offset0:8 offset1:12
	ds_read2_b64 v[126:129], v138 offset0:24 offset1:28
	ds_read2_b64 v[130:133], v139 offset0:40 offset1:44
	ds_read2_b64 v[134:137], v140 offset0:56 offset1:60
	v_sub_f32_e32 v89, v89, v193
	v_sub_f32_e32 v88, v88, v193
	v_exp_f32_e32 v117, v91
	v_exp_f32_e32 v118, v89
	v_exp_f32_e32 v119, v88
	v_cvt_pk_bf16_f32 v125, v121, v120
	v_cvt_pk_bf16_f32 v138, v113, v112
	v_cvt_pk_bf16_f32 v139, v114, v115
	v_cvt_pk_bf16_f32 v140, v116, v117
	v_cvt_pk_bf16_f32 v141, v118, v119
	s_setprio 1
	s_waitcnt lgkmcnt(3)
	v_mfma_f32_16x16x32_bf16 v[88:91], v[100:103], v[122:125], v[84:87]
	v_mfma_f32_16x16x32_bf16 v[96:99], v[100:103], v[138:141], v[96:99]
	s_waitcnt lgkmcnt(2)
	v_mfma_f32_16x16x32_bf16 v[100:103], v[126:129], v[122:125], v[80:83]
	v_mfma_f32_16x16x32_bf16 v[84:87], v[126:129], v[138:141], v[92:95]
	s_waitcnt lgkmcnt(1)
	v_mfma_f32_16x16x32_bf16 v[92:95], v[130:133], v[122:125], v[76:79]
	v_mfma_f32_16x16x32_bf16 v[76:79], v[130:133], v[138:141], v[108:111]
	s_waitcnt lgkmcnt(0)
	v_mfma_f32_16x16x32_bf16 v[80:83], v[134:137], v[122:125], v[72:75]
	v_mfma_f32_16x16x32_bf16 v[72:75], v[134:137], v[138:141], v[104:107]
	s_setprio 0
	s_xor_b32 s46, s46, 1
	s_cmp_lt_i32 s16, 0
	s_cbranch_scc1 .LBB0_375
	v_mov_b32 v104, v179
	s_lshl_b32 s17, s46, 13
	v_ashrrev_i32_e32 v105, 3, v104
	v_xor_b32_e32 v107, v105, v104
	v_lshl_add_u32 v106, v105, 7, s17
	v_lshlrev_b32_e32 v107, 4, v107
	s_movk_i32 s30, 0x70
	v_lshlrev_b32_e32 v104, 3, v104
	v_and_or_b32 v106, v107, s30, v106
	s_lshl_b32 s30, s46, 9
	v_and_b32_e32 v104, 56, v104
	s_add_i32 s17, s17, s30
	v_mul_u32_u24_e32 v104, 0x88, v104
	v_lshlrev_b32_e32 v105, 1, v105
	v_add3_u32 v104, s17, v104, v105
	s_waitcnt vmcnt(1)
	ds_write_b128 v106, v[56:59]
	s_waitcnt vmcnt(0)
	ds_write_b16 v104, v60 offset:16384
	ds_write_b16_d16_hi v104, v60 offset:16520
	ds_write_b16 v104, v61 offset:16656
	ds_write_b16_d16_hi v104, v61 offset:16792
	ds_write_b16 v104, v62 offset:16928
	ds_write_b16_d16_hi v104, v62 offset:17064
	ds_write_b16 v104, v63 offset:17200
	ds_write_b16_d16_hi v104, v63 offset:17336

; template <int MODE>
; __device__ __forceinline__ void nsa_compute(int cur, int buf, int t, int hl, u64 mymask, const bf16x8 (&Qf)[2][2], f32x4 (&O)[4][2], float (&m)[2], float (&l)[2],
;                                             const float (&inv)[2], float* impw, char* lds) {
;     ...
;     for (int r = 0; r < 2; ++r) {
;       float sv[2][4];
; #pragma unroll
;       for (int kk = 0; kk < 2; ++kk)
; #pragma unroll
;         for (int e = 0; e < 4; ++e) {
;           const int off = 32 * s2 + 16 * kk + e;
;           int idx;
;           if (MODE <= 1) { idx = base - 16 * off; idx = idx > 0 ? idx : 0; } else idx = base - off;
;           sv[kk][e] = S[kk][r][e] * (0.125f * LOG2E) + tb[r * TS + idx];
;         }
;       float pv[2][4];
;       if (MODE == 1) {
; #pragma unroll
;         for (int kk = 0; kk < 2; ++kk)
; #pragma unroll
;           for (int e = 0; e < 4; ++e) pv[kk][e] = __builtin_amdgcn_exp2f(sv[kk][e] - m[r]) * inv[r];
; #pragma unroll
;         for (int kk = 0; kk < 2; ++kk) { g1s[kk] += pv[kk][0] + pv[kk][1] + pv[kk][2] + 0.5f * pv[kk][3]; p3s[kk] += 0.5f * pv[kk][3]; }
;       } else {
;         const float mxa = fmaxf(fmaxf(sv[0][0], sv[0][1]), sv[0][2]), mxb = fmaxf(fmaxf(sv[0][3], sv[1][0]), sv[1][1]);
;         float mx = fmaxf(fmaxf(fmaxf(sv[1][2], sv[1][3]), mxa), mxb);
;         if (MODE == 2) mx = selok ? mx : -__builtin_inff();
;         if (__any(mx > m[r] + 8.0f)) {
;           mx = fmaxf(mx, __shfl_xor(mx, 16)); mx = fmaxf(mx, __shfl_xor(mx, 32));
;           const float mn = fmaxf(m[r], mx), al = __builtin_amdgcn_exp2f(m[r] - mn);
;           m[r] = mn; l[r] *= al;
;           if (MODE != 0) {
; #pragma unroll
;             for (int df = 0; df < 4; ++df) O[df][r] *= al;
;           }
;         }
;         const float me = (MODE == 2) ? (selok ? m[r] : __builtin_inff()) : m[r];
;         float ps = 0.f;
; #pragma unroll
;         for (int kk = 0; kk < 2; ++kk)
; #pragma unroll
;           for (int e = 0; e < 4; ++e) { pv[kk][e] = __builtin_amdgcn_exp2f(sv[kk][e] - me); ps += pv[kk][e]; }
;         l[r] += ps;
;       }
;       if (MODE != 0) {
;         const unsigned w0 = pk2(pv[0][0], pv[0][1]), w1 = pk2(pv[0][2], pv[0][3]), w2 = pk2(pv[1][0], pv[1][1]), w3 = pk2(pv[1][2], pv[1][3]);
;         u32x4 pw; pw.x = w0; pw.y = w1; pw.z = w2; pw.w = w3;
;         Pf[r] = __builtin_bit_cast(bf16x8, pw);
;       }
;     }
.LBB0_385:
	v_sub_f32_e32 v119, v135, v193
	v_exp_f32_e32 v119, v119
	v_sub_f32_e32 v134, v134, v193
	v_exp_f32_e32 v134, v134
	v_sub_f32_e32 v145, v145, v193
	v_exp_f32_e32 v145, v145
	v_sub_f32_e32 v144, v144, v193
	v_exp_f32_e32 v144, v144
	v_sub_f32_e32 v133, v133, v193
	v_exp_f32_e32 v133, v133
	v_sub_f32_e32 v132, v132, v193
	v_add_f32_e32 v135, v134, v119
	v_exp_f32_e32 v132, v132
	v_sub_f32_e32 v117, v117, v193
	v_add_f32_e32 v135, v145, v135
	v_exp_f32_e32 v117, v117
	v_sub_f32_e32 v116, v116, v193
	v_add_f32_e32 v135, v144, v135
	v_exp_f32_e32 v116, v116
	v_add_f32_e32 v135, v133, v135
	v_add_f32_e32 v135, v132, v135
	v_add_f32_e32 v135, v117, v135
	s_lshl_b32 s16, s46, 9
	v_add_f32_e32 v118, v116, v135
	v_cvt_pk_bf16_f32 v167, v117, v116
	v_mul_u32_u24_e32 v116, 0x44, v149
	s_add_i32 s72, s71, s16
	v_lshlrev_b32_e32 v116, 1, v116
	v_lshlrev_b32_e32 v117, 1, v150
	v_add3_u32 v116, s72, v116, v117
	v_cvt_pk_bf16_f32 v161, v153, v155
	v_cvt_pk_bf16_f32 v162, v156, v157
	v_add_u32_e32 v155, 0x4000, v116
	v_add_u32_e32 v156, 0x4800, v116
	v_cvt_pk_bf16_f32 v160, v151, v152
	v_cvt_pk_bf16_f32 v163, v158, v159
	v_cvt_pk_bf16_f32 v164, v119, v134
	v_cvt_pk_bf16_f32 v166, v133, v132
	ds_read2_b64 v[132:135], v155 offset1:4
	ds_read2_b64 v[150:153], v156 offset0:16 offset1:20
	v_add_u32_e32 v157, 0x5000, v116
	v_add_u32_e32 v158, 0x5800, v116
	ds_read2_b64 v[168:171], v157 offset0:32 offset1:36
	ds_read2_b64 v[172:175], v158 offset0:48 offset1:52
	v_add_f32_e32 v197, v197, v118
	v_cvt_pk_bf16_f32 v165, v145, v144
	s_setprio 1
	s_waitcnt lgkmcnt(3)
	v_mfma_f32_16x16x32_bf16 v[116:119], v[132:135], v[160:163], v[112:115]
	v_mfma_f32_16x16x32_bf16 v[132:135], v[132:135], v[164:167], v[124:127]
	s_waitcnt lgkmcnt(2)
	v_mfma_f32_16x16x32_bf16 v[112:115], v[150:153], v[160:163], v[104:107]
	v_mfma_f32_16x16x32_bf16 v[128:131], v[150:153], v[164:167], v[128:131]
	s_waitcnt lgkmcnt(1)
	v_mfma_f32_16x16x32_bf16 v[108:111], v[168:171], v[160:163], v[108:111]
	v_mfma_f32_16x16x32_bf16 v[124:127], v[168:171], v[164:167], v[136:139]
	s_waitcnt lgkmcnt(0)
	v_mfma_f32_16x16x32_bf16 v[104:107], v[172:175], v[160:163], v[120:123]
	v_mfma_f32_16x16x32_bf16 v[120:123], v[172:175], v[164:167], v[140:143]
	s_setprio 0
	s_nop 1
	v_add_u32_e32 v140, v147, v146
	v_add_u32_e32 v148, v148, v146
	ds_read_b128 v[136:139], v140 offset:4096
	ds_read_b128 v[140:143], v140 offset:6144
	ds_read_b128 v[144:147], v148 offset:4096
	ds_read_b128 v[148:151], v148 offset:6144
	v_add_u32_e32 v251, 0xa00, v154
	ds_read2_b32 v[202:203], v154 offset0:31 offset1:32
	ds_read2_b32 v[204:205], v154 offset0:29 offset1:30
	ds_read2_b32 v[206:207], v154 offset0:15 offset1:16
	ds_read2_b32 v[208:209], v154 offset0:13 offset1:14
	ds_read2_b32 v[210:211], v251 offset0:31 offset1:32
	ds_read2_b32 v[236:237], v251 offset0:29 offset1:30
	ds_read2_b32 v[238:239], v251 offset0:15 offset1:16
	ds_read2_b32 v[240:241], v251 offset0:13 offset1:14
	s_setprio 1
	s_waitcnt lgkmcnt(11)
	v_mfma_f32_16x16x32_bf16 v[160:163], v[136:139], v[0:3], 0
	v_mfma_f32_16x16x32_bf16 v[136:139], v[136:139], v[8:11], 0
	s_waitcnt lgkmcnt(10)
	v_mfma_f32_16x16x32_bf16 v[168:171], v[140:143], v[8:11], 0
	v_mfma_f32_16x16x32_bf16 v[164:167], v[140:143], v[0:3], 0
	s_waitcnt lgkmcnt(9)
	v_mfma_f32_16x16x32_bf16 v[160:163], v[144:147], v[4:7], v[160:163]
	v_mfma_f32_16x16x32_bf16 v[140:143], v[144:147], v[12:15], v[136:139]
	s_waitcnt lgkmcnt(8)
	v_mfma_f32_16x16x32_bf16 v[136:139], v[148:151], v[12:15], v[168:171]
	v_mfma_f32_16x16x32_bf16 v[164:167], v[148:151], v[4:7], v[164:167]
	s_setprio 0
	s_waitcnt lgkmcnt(7)
	s_nop 1
	v_fmamk_f32 v160, v160, 0x3e38aa3b, v203
	v_fmamk_f32 v150, v161, 0x3e38aa3b, v202
	s_waitcnt lgkmcnt(6)
	v_fmamk_f32 v159, v162, 0x3e38aa3b, v205
	v_fmamk_f32 v148, v163, 0x3e38aa3b, v204
	s_waitcnt lgkmcnt(5)
	v_fmamk_f32 v151, v164, 0x3e38aa3b, v207
	v_fmamk_f32 v146, v165, 0x3e38aa3b, v206
	s_waitcnt lgkmcnt(4)
	v_fmamk_f32 v145, v166, 0x3e38aa3b, v209
	v_fmamk_f32 v144, v167, 0x3e38aa3b, v208
	v_max3_f32 v147, v160, v150, v159
	v_max3_f32 v149, v148, v151, v146
	v_max_f32_e32 v152, v145, v144
	v_max3_f32 v147, v152, v147, v149
	v_add_f32_e32 v149, 0x41000000, v192
	v_cmp_gt_f32_e32 vcc, v147, v149
	s_cbranch_vccz .LBB0_387
	ds_bpermute_b32 v149, v233, v147
	v_max_f32_e32 v147, v147, v147
	v_mov_b32_e32 v153, v193
	s_waitcnt lgkmcnt(0)
	v_max_f32_e32 v149, v149, v149
	v_max_f32_e32 v147, v147, v149
	ds_bpermute_b32 v149, v234, v147
	s_waitcnt lgkmcnt(0)
	v_max3_f32 v152, v192, v147, v149
	v_sub_f32_e32 v147, v192, v152
	v_exp_f32_e32 v162, v147
	v_mov_b64_e32 v[192:193], v[152:153]
	v_mul_f32_e32 v196, v196, v162
	v_pk_mul_f32 v[118:119], v[118:119], v[162:163] op_sel_hi:[1,0]
	v_pk_mul_f32 v[116:117], v[116:117], v[162:163] op_sel_hi:[1,0]
	v_pk_mul_f32 v[114:115], v[114:115], v[162:163] op_sel_hi:[1,0]
	v_pk_mul_f32 v[112:113], v[112:113], v[162:163] op_sel_hi:[1,0]
	v_pk_mul_f32 v[110:111], v[110:111], v[162:163] op_sel_hi:[1,0]
	v_pk_mul_f32 v[108:109], v[108:109], v[162:163] op_sel_hi:[1,0]
	v_pk_mul_f32 v[106:107], v[106:107], v[162:163] op_sel_hi:[1,0]
	v_pk_mul_f32 v[104:105], v[104:105], v[162:163] op_sel_hi:[1,0]
	s_branch .LBB0_388

; template <int MODE>
; __device__ __forceinline__ void nsa_compute(int cur, int buf, int t, int hl, u64 mymask, const bf16x8 (&Qf)[2][2], f32x4 (&O)[4][2], float (&m)[2], float (&l)[2],
;                                             const float (&inv)[2], float* impw, char* lds) {
;     ...
;     for (int r = 0; r < 2; ++r) {
;       float sv[2][4];
; #pragma unroll
;       for (int kk = 0; kk < 2; ++kk)
; #pragma unroll
;         for (int e = 0; e < 4; ++e) {
;           const int off = 32 * s2 + 16 * kk + e;
;           int idx;
;           if (MODE <= 1) { idx = base - 16 * off; idx = idx > 0 ? idx : 0; } else idx = base - off;
;           sv[kk][e] = S[kk][r][e] * (0.125f * LOG2E) + tb[r * TS + idx];
;         }
;       float pv[2][4];
;       if (MODE == 1) {
; #pragma unroll
;         for (int kk = 0; kk < 2; ++kk)
; #pragma unroll
;           for (int e = 0; e < 4; ++e) pv[kk][e] = __builtin_amdgcn_exp2f(sv[kk][e] - m[r]) * inv[r];
; #pragma unroll
;         for (int kk = 0; kk < 2; ++kk) { g1s[kk] += pv[kk][0] + pv[kk][1] + pv[kk][2] + 0.5f * pv[kk][3]; p3s[kk] += 0.5f * pv[kk][3]; }
;       } else {
;         const float mxa = fmaxf(fmaxf(sv[0][0], sv[0][1]), sv[0][2]), mxb = fmaxf(fmaxf(sv[0][3], sv[1][0]), sv[1][1]);
;         float mx = fmaxf(fmaxf(fmaxf(sv[1][2], sv[1][3]), mxa), mxb);
;         if (MODE == 2) mx = selok ? mx : -__builtin_inff();
;         if (__any(mx > m[r] + 8.0f)) {
;           mx = fmaxf(mx, __shfl_xor(mx, 16)); mx = fmaxf(mx, __shfl_xor(mx, 32));
;           const float mn = fmaxf(m[r], mx), al = __builtin_amdgcn_exp2f(m[r] - mn);
;           m[r] = mn; l[r] *= al;
;           if (MODE != 0) {
; #pragma unroll
;             for (int df = 0; df < 4; ++df) O[df][r] *= al;
;           }
;         }
;         const float me = (MODE == 2) ? (selok ? m[r] : __builtin_inff()) : m[r];
;         float ps = 0.f;
; #pragma unroll
;         for (int kk = 0; kk < 2; ++kk)
; #pragma unroll
;           for (int e = 0; e < 4; ++e) { pv[kk][e] = __builtin_amdgcn_exp2f(sv[kk][e] - me); ps += pv[kk][e]; }
;         l[r] += ps;
;       }
;       if (MODE != 0) {
;         const unsigned w0 = pk2(pv[0][0], pv[0][1]), w1 = pk2(pv[0][2], pv[0][3]), w2 = pk2(pv[1][0], pv[1][1]), w3 = pk2(pv[1][2], pv[1][3]);
;         u32x4 pw; pw.x = w0; pw.y = w1; pw.z = w2; pw.w = w3;
;         Pf[r] = __builtin_bit_cast(bf16x8, pw);
;       }
;     }
.LBB0_402:
	v_sub_f32_e32 v173, v173, v193
	v_exp_f32_e32 v173, v173
	v_sub_f32_e32 v172, v172, v193
	v_exp_f32_e32 v172, v172
	v_sub_f32_e32 v175, v175, v193
	v_exp_f32_e32 v175, v175
	v_sub_f32_e32 v174, v174, v193
	v_exp_f32_e32 v174, v174
	v_sub_f32_e32 v125, v125, v193
	v_cvt_pk_bf16_f32 v202, v202, v203
	v_cvt_pk_bf16_f32 v203, v204, v205
	v_cvt_pk_bf16_f32 v204, v206, v207
	v_exp_f32_e32 v125, v125
	v_sub_f32_e32 v124, v124, v193
	v_add_f32_e32 v206, v172, v173
	v_exp_f32_e32 v124, v124
	v_add_f32_e32 v206, v175, v206
	v_add_f32_e32 v206, v174, v206
	v_sub_f32_e32 v127, v127, v193
	v_add_f32_e32 v206, v125, v206
	v_exp_f32_e32 v127, v127
	v_sub_f32_e32 v126, v126, v193
	v_add_f32_e32 v206, v124, v206
	v_exp_f32_e32 v126, v126
	v_cvt_pk_bf16_f32 v172, v173, v172
	v_cvt_pk_bf16_f32 v173, v175, v174
	v_cvt_pk_bf16_f32 v174, v125, v124
	v_mul_u32_u24_e32 v124, 0x44, v200
	v_lshlrev_b32_e32 v124, 1, v124
	v_lshlrev_b32_e32 v125, 1, v201
	v_add3_u32 v200, s43, v124, v125
	v_cvt_pk_bf16_f32 v205, v236, v237
	v_add_f32_e32 v206, v127, v206
	v_add_u32_e32 v236, 0x4000, v200
	v_add_u32_e32 v237, 0x4800, v200
	v_add_f32_e32 v206, v126, v206
	v_cvt_pk_bf16_f32 v175, v127, v126
	ds_read2_b64 v[124:127], v236 offset1:4
	ds_read2_b64 v[240:243], v237 offset0:16 offset1:20
	v_add_u32_e32 v238, 0x5000, v200
	v_add_u32_e32 v239, 0x5800, v200
	ds_read2_b64 v[244:247], v238 offset0:32 offset1:36
	ds_read2_b64 v[248:251], v239 offset0:48 offset1:52
	v_add_f32_e32 v191, v191, v206
	s_setprio 1
	s_waitcnt lgkmcnt(3)
	v_mfma_f32_16x16x32_bf16 v[104:107], v[124:127], v[202:205], v[104:107]
	v_mfma_f32_16x16x32_bf16 v[124:127], v[124:127], v[172:175], v[120:123]
	s_waitcnt lgkmcnt(2)
	v_mfma_f32_16x16x32_bf16 v[108:111], v[240:243], v[202:205], v[108:111]
	v_mfma_f32_16x16x32_bf16 v[128:131], v[240:243], v[172:175], v[128:131]
	s_waitcnt lgkmcnt(1)
	v_mfma_f32_16x16x32_bf16 v[112:115], v[244:247], v[202:205], v[112:115]
	v_mfma_f32_16x16x32_bf16 v[132:135], v[244:247], v[172:175], v[132:135]
	s_waitcnt lgkmcnt(0)
	v_mfma_f32_16x16x32_bf16 v[120:123], v[248:251], v[202:205], v[116:119]
	v_mfma_f32_16x16x32_bf16 v[168:171], v[248:251], v[172:175], v[168:171]
	s_setprio 0
	s_nop 0
	ds_read_b128 v[116:119], v198 offset:4096
	ds_read_b128 v[172:175], v198 offset:6144
	ds_read_b128 v[200:203], v199 offset:4096
	ds_read_b128 v[204:207], v199 offset:6144
	s_setprio 1
	s_waitcnt lgkmcnt(3)
	v_mfma_f32_16x16x32_bf16 v[240:243], v[116:119], v[0:3], 0
	v_mfma_f32_16x16x32_bf16 v[116:119], v[116:119], v[8:11], 0
	s_waitcnt lgkmcnt(2)
	v_mfma_f32_16x16x32_bf16 v[248:251], v[172:175], v[8:11], 0
	v_mfma_f32_16x16x32_bf16 v[244:247], v[172:175], v[0:3], 0
	s_waitcnt lgkmcnt(1)
	v_mfma_f32_16x16x32_bf16 v[172:175], v[200:203], v[12:15], v[116:119]
	s_waitcnt lgkmcnt(0)
	v_mfma_f32_16x16x32_bf16 v[116:119], v[204:207], v[12:15], v[248:251]
	v_mfma_f32_16x16x32_bf16 v[208:211], v[200:203], v[4:7], v[240:243]
	v_mfma_f32_16x16x32_bf16 v[242:245], v[204:207], v[4:7], v[244:247]
	s_setprio 0
	ds_read2_b32 v[204:205], v176 offset0:31 offset1:32
	ds_read2_b32 v[202:203], v176 offset0:29 offset1:30
	ds_read2_b32 v[200:201], v176 offset0:15 offset1:16
	ds_read2_b32 v[198:199], v176 offset0:13 offset1:14
	s_waitcnt lgkmcnt(3)
	s_nop 0
	v_fmamk_f32 v241, v208, 0x3e38aa3b, v205
	v_fmac_f32_e32 v204, 0x3e38aa3b, v209
	s_waitcnt lgkmcnt(2)
	v_fmamk_f32 v240, v210, 0x3e38aa3b, v203
	v_fmac_f32_e32 v202, 0x3e38aa3b, v211
	s_waitcnt lgkmcnt(1)
	v_fmamk_f32 v205, v242, 0x3e38aa3b, v201
	v_fmac_f32_e32 v200, 0x3e38aa3b, v243
	s_waitcnt lgkmcnt(0)
	v_fmamk_f32 v199, v244, 0x3e38aa3b, v199
	v_fmac_f32_e32 v198, 0x3e38aa3b, v245
	v_max3_f32 v201, v241, v204, v240
	v_max3_f32 v203, v202, v205, v200
	v_max_f32_e32 v206, v199, v198
	v_max3_f32 v201, v206, v201, v203
	v_add_f32_e32 v203, 0x41000000, v192
	v_cmp_gt_f32_e32 vcc, v201, v203
	s_cbranch_vccz .LBB0_404
	ds_bpermute_b32 v203, v233, v201
	v_max_f32_e32 v201, v201, v201
	v_mov_b32_e32 v207, v193
	s_waitcnt lgkmcnt(0)
	v_max_f32_e32 v203, v203, v203
	v_max_f32_e32 v201, v201, v203
	ds_bpermute_b32 v203, v234, v201
	s_waitcnt lgkmcnt(0)
	v_max3_f32 v206, v192, v201, v203
	v_sub_f32_e32 v192, v192, v206
	v_exp_f32_e32 v192, v192
	s_nop 0
	v_mul_f32_e32 v190, v190, v192
	v_pk_mul_f32 v[106:107], v[106:107], v[192:193] op_sel_hi:[1,0]
	v_pk_mul_f32 v[104:105], v[104:105], v[192:193] op_sel_hi:[1,0]
	v_pk_mul_f32 v[110:111], v[110:111], v[192:193] op_sel_hi:[1,0]
	v_pk_mul_f32 v[108:109], v[108:109], v[192:193] op_sel_hi:[1,0]
	v_pk_mul_f32 v[114:115], v[114:115], v[192:193] op_sel_hi:[1,0]
	v_pk_mul_f32 v[112:113], v[112:113], v[192:193] op_sel_hi:[1,0]
	v_pk_mul_f32 v[122:123], v[122:123], v[192:193] op_sel_hi:[1,0]
	v_pk_mul_f32 v[120:121], v[120:121], v[192:193] op_sel_hi:[1,0]
	v_mov_b64_e32 v[192:193], v[206:207]
	s_branch .LBB0_405

; #define TIDX opaque_tid()
; __device__ __forceinline__ unsigned pk2(float lo, float hi) { const f32x2v v = {lo, hi}; const bf16x2v r = __builtin_convertvector(v, bf16x2v); return __builtin_bit_cast(unsigned, r); }
; __device__ __forceinline__ void kv_lwrite(const KVRegs& r, char* lds, int buf) {
;   const int tid = TIDX, row = tid >> 3, cq = tid & 7;
;   char* kt = lds + NSA_KT + buf * 8192 + row * 128;
;   *(u32x4*)(kt + ((cq ^ (row & 7)) << 4)) = r.k0;
;   bf16_t* vt = (bf16_t*)(lds + NSA_VT + buf * 8704) + (cq * 8) * 68 + row;
; #pragma unroll
;   for (int i = 0; i < 4; ++i) { vt[(2 * i) * 68] = (bf16_t)(r.v0[i] & 0xffffu); vt[(2 * i + 1) * 68] = (bf16_t)(r.v0[i] >> 16); }
; }
; template <int MODE>
; __device__ __forceinline__ void nsa_compute(int cur, int buf, int t, int hl, u64 mymask, const bf16x8 (&Qf)[2][2], f32x4 (&O)[4][2], float (&m)[2], float (&l)[2],
;                                             const float (&inv)[2], float* impw, char* lds) {
;     ...
;         const float me = (MODE == 2) ? (selok ? m[r] : __builtin_inff()) : m[r];
;         float ps = 0.f;
; #pragma unroll
;         for (int kk = 0; kk < 2; ++kk)
; #pragma unroll
;           for (int e = 0; e < 4; ++e) { pv[kk][e] = __builtin_amdgcn_exp2f(sv[kk][e] - me); ps += pv[kk][e]; }
;         l[r] += ps;
;       }
;       if (MODE != 0) {
;         const unsigned w0 = pk2(pv[0][0], pv[0][1]), w1 = pk2(pv[0][2], pv[0][3]), w2 = pk2(pv[1][0], pv[1][1]), w3 = pk2(pv[1][2], pv[1][3]);
;         u32x4 pw; pw.x = w0; pw.y = w1; pw.z = w2; pw.w = w3;
;         Pf[r] = __builtin_bit_cast(bf16x8, pw);
;       }
;     }
;     if (MODE != 0) {
;       bf16x8 vfr[4];
; #pragma unroll
;       for (int df = 0; df < 4; ++df) {
;         const bf16x4 va = *(const bf16x4*)(vt + (df * 16 + fr) * 68 + 32 * s2 + 4 * fq);
;         const bf16x4 vb = *(const bf16x4*)(vt + (df * 16 + fr) * 68 + 32 * s2 + 16 + 4 * fq);
;         bf16x8 vf; vf[0] = va[0]; vf[1] = va[1]; vf[2] = va[2]; vf[3] = va[3]; vf[4] = vb[0]; vf[5] = vb[1]; vf[6] = vb[2]; vf[7] = vb[3];
;         vfr[df] = vf;
;       }
;       __builtin_amdgcn_s_setprio(1);
; #pragma unroll
;       for (int df = 0; df < 4; ++df)
; #pragma unroll
;         for (int r = 0; r < 2; ++r) O[df][r] = mfma16(vfr[df], Pf[r], O[df][r]);
;       __builtin_amdgcn_s_setprio(0);
;     }
.LBB0_448:
	v_cndmask_b32_e64 v91, v189, v228, s[36:37]
	v_cvt_pk_bf16_f32 v104, v47, v84
	v_cvt_pk_bf16_f32 v105, v85, v46
	v_cvt_pk_bf16_f32 v106, v87, v88
	v_cvt_pk_bf16_f32 v107, v89, v86
	v_sub_f32_e32 v37, v45, v91
	v_sub_f32_e32 v38, v44, v91
	ds_read2_b64 v[44:47], v94 offset0:8 offset1:12
	ds_read2_b64 v[84:87], v95 offset0:24 offset1:28
	ds_read2_b64 v[108:111], v96 offset0:40 offset1:44
	ds_read2_b64 v[112:115], v97 offset0:56 offset1:60
	v_sub_f32_e32 v39, v41, v91
	v_sub_f32_e32 v40, v40, v91
	v_sub_f32_e32 v41, v43, v91
	v_sub_f32_e32 v42, v42, v91
	v_sub_f32_e32 v43, v90, v91
	v_sub_f32_e32 v36, v36, v91
	v_exp_f32_e32 v37, v37
	v_exp_f32_e32 v38, v38
	v_exp_f32_e32 v39, v39
	v_exp_f32_e32 v40, v40
	v_exp_f32_e32 v41, v41
	v_exp_f32_e32 v42, v42
	v_exp_f32_e32 v43, v43
	v_exp_f32_e32 v36, v36
	v_cvt_pk_bf16_f32 v116, v37, v38
	v_cvt_pk_bf16_f32 v117, v39, v40
	v_cvt_pk_bf16_f32 v118, v41, v42
	v_cvt_pk_bf16_f32 v119, v43, v36
	s_setprio 1
	s_waitcnt lgkmcnt(3)
	v_mfma_f32_16x16x32_bf16 v[88:91], v[44:47], v[104:107], v[72:75]
	v_mfma_f32_16x16x32_bf16 v[96:99], v[44:47], v[116:119], v[80:83]
	s_waitcnt lgkmcnt(2)
	v_mfma_f32_16x16x32_bf16 v[100:103], v[84:87], v[104:107], v[24:27]
	v_mfma_f32_16x16x32_bf16 v[84:87], v[84:87], v[116:119], v[76:79]
	s_waitcnt lgkmcnt(1)
	v_mfma_f32_16x16x32_bf16 v[92:95], v[108:111], v[104:107], v[20:23]
	v_mfma_f32_16x16x32_bf16 v[76:79], v[108:111], v[116:119], v[32:35]
	s_waitcnt lgkmcnt(0)
	v_mfma_f32_16x16x32_bf16 v[80:83], v[112:115], v[104:107], v[16:19]
	v_mfma_f32_16x16x32_bf16 v[72:75], v[112:115], v[116:119], v[28:31]
	s_setprio 0
	s_xor_b32 s74, s74, 1
	s_cmp_lt_i32 s16, 0
	s_cbranch_scc1 .LBB0_450
	v_mov_b32 v16, v179
	s_lshl_b32 s17, s74, 13
	v_ashrrev_i32_e32 v17, 3, v16
	v_xor_b32_e32 v19, v17, v16
	v_lshl_add_u32 v18, v17, 7, s17
	v_lshlrev_b32_e32 v19, 4, v19
	s_movk_i32 s30, 0x70
	v_lshlrev_b32_e32 v16, 3, v16
	v_and_or_b32 v18, v19, s30, v18
	s_lshl_b32 s30, s74, 9
	v_and_b32_e32 v16, 56, v16
	s_add_i32 s17, s17, s30
	v_mul_u32_u24_e32 v16, 0x88, v16
	v_lshlrev_b32_e32 v17, 1, v17
	v_add3_u32 v16, s17, v16, v17
	s_waitcnt vmcnt(1)
	ds_write_b128 v18, v[56:59]
	s_waitcnt vmcnt(0)
	ds_write_b16 v16, v60 offset:16384
	ds_write_b16_d16_hi v16, v60 offset:16520
	ds_write_b16 v16, v61 offset:16656
	ds_write_b16_d16_hi v16, v61 offset:16792
	ds_write_b16 v16, v62 offset:16928
	ds_write_b16_d16_hi v16, v62 offset:17064
	ds_write_b16 v16, v63 offset:17200
	ds_write_b16_d16_hi v16, v63 offset:17336

; template <int MODE>
; __device__ __forceinline__ void nsa_compute(int cur, int buf, int t, int hl, u64 mymask, const bf16x8 (&Qf)[2][2], f32x4 (&O)[4][2], float (&m)[2], float (&l)[2],
;                                             const float (&inv)[2], float* impw, char* lds) {
;     ...
;         const float mxa = fmaxf(fmaxf(sv[0][0], sv[0][1]), sv[0][2]), mxb = fmaxf(fmaxf(sv[0][3], sv[1][0]), sv[1][1]);
;         float mx = fmaxf(fmaxf(fmaxf(sv[1][2], sv[1][3]), mxa), mxb);
;         if (MODE == 2) mx = selok ? mx : -__builtin_inff();
;         if (__any(mx > m[r] + 8.0f)) {
;           mx = fmaxf(mx, __shfl_xor(mx, 16)); mx = fmaxf(mx, __shfl_xor(mx, 32));
;           const float mn = fmaxf(m[r], mx), al = __builtin_amdgcn_exp2f(m[r] - mn);
;           m[r] = mn; l[r] *= al;
;           if (MODE != 0) {
; #pragma unroll
;             for (int df = 0; df < 4; ++df) O[df][r] *= al;
;           }
;         }
;         const float me = (MODE == 2) ? (selok ? m[r] : __builtin_inff()) : m[r];
;         float ps = 0.f;
; #pragma unroll
;         for (int kk = 0; kk < 2; ++kk)
; #pragma unroll
;           for (int e = 0; e < 4; ++e) { pv[kk][e] = __builtin_amdgcn_exp2f(sv[kk][e] - me); ps += pv[kk][e]; }
;         l[r] += ps;
.LBB0_456:
	v_cndmask_b32_e64 v104, v188, v228, s[36:37]
	v_sub_f32_e32 v47, v47, v104
	v_exp_f32_e32 v119, v47
	v_sub_f32_e32 v46, v46, v104
	v_exp_f32_e32 v120, v46
	v_sub_f32_e32 v43, v43, v104
	v_exp_f32_e32 v121, v43
	v_sub_f32_e32 v42, v42, v104
	v_exp_f32_e32 v123, v42
	v_sub_f32_e32 v41, v41, v104
	v_add_f32_e32 v47, 0, v119
	v_exp_f32_e32 v124, v41
	v_sub_f32_e32 v40, v40, v104
	v_add_f32_e32 v46, v120, v47
	v_exp_f32_e32 v125, v40
	v_add_f32_e32 v43, v121, v46
	v_add_f32_e32 v42, v123, v43
	v_add_f32_e32 v41, v124, v42
	v_add_f32_e32 v40, v125, v41
	v_sub_f32_e32 v41, v45, v104
	v_exp_f32_e32 v126, v41
	v_sub_f32_e32 v41, v44, v104
	v_exp_f32_e32 v127, v41
	v_add_f32_e32 v40, v126, v40
	v_add_f32_e32 v40, v127, v40
	v_add_f32_e32 v146, v146, v40
	s_waitcnt lgkmcnt(3)
	v_fmamk_f32 v47, v36, 0x3e38aa3b, v157
	v_fmamk_f32 v46, v37, 0x3e38aa3b, v156
	s_waitcnt lgkmcnt(2)
	v_fmamk_f32 v113, v38, 0x3e38aa3b, v169
	v_fmamk_f32 v112, v39, 0x3e38aa3b, v168
	s_waitcnt lgkmcnt(1)
	v_fmamk_f32 v45, v28, 0x3e38aa3b, v171
	v_fmamk_f32 v44, v29, 0x3e38aa3b, v170
	s_waitcnt lgkmcnt(0)
	v_fmamk_f32 v29, v30, 0x3e38aa3b, v173
	v_fmamk_f32 v28, v31, 0x3e38aa3b, v172
	v_max3_f32 v30, v47, v46, v113
	v_max3_f32 v31, v112, v45, v44
	v_max_f32_e32 v36, v29, v28
	v_max3_f32 v30, v36, v30, v31
	v_cndmask_b32_e64 v30, v30, v225, s[36:37]
	v_add_f32_e32 v31, 0x41000000, v189
	v_cmp_gt_f32_e32 vcc, v30, v31
	s_cbranch_vccz .LBB0_458
	ds_bpermute_b32 v31, v233, v30
	v_max_f32_e32 v30, v30, v30
	s_waitcnt lgkmcnt(0)
	v_max_f32_e32 v31, v31, v31
	v_max_f32_e32 v30, v30, v31
	ds_bpermute_b32 v31, v234, v30
	s_waitcnt lgkmcnt(0)
	v_max3_f32 v30, v189, v30, v31
	v_sub_f32_e32 v31, v189, v30
	v_exp_f32_e32 v108, v31
	v_mov_b32_e32 v189, v30
	v_mul_f32_e32 v147, v147, v108
	v_pk_mul_f32 v[38:39], v[98:99], v[108:109] op_sel_hi:[1,0]
	v_pk_mul_f32 v[36:37], v[96:97], v[108:109] op_sel_hi:[1,0]
	v_pk_mul_f32 v[42:43], v[86:87], v[108:109] op_sel_hi:[1,0]
	v_pk_mul_f32 v[40:41], v[84:85], v[108:109] op_sel_hi:[1,0]
	v_pk_mul_f32 v[106:107], v[78:79], v[108:109] op_sel_hi:[1,0]
	v_pk_mul_f32 v[104:105], v[76:77], v[108:109] op_sel_hi:[1,0]
	v_pk_mul_f32 v[110:111], v[74:75], v[108:109] op_sel_hi:[1,0]
	v_pk_mul_f32 v[108:109], v[72:73], v[108:109] op_sel_hi:[1,0]
	s_branch .LBB0_459

; template <int MODE>
; __device__ __forceinline__ void nsa_compute(int cur, int buf, int t, int hl, u64 mymask, const bf16x8 (&Qf)[2][2], f32x4 (&O)[4][2], float (&m)[2], float (&l)[2],
;                                             const float (&inv)[2], float* impw, char* lds) {
;     ...
;     for (int r = 0; r < 2; ++r) {
;       float sv[2][4];
; #pragma unroll
;       for (int kk = 0; kk < 2; ++kk)
; #pragma unroll
;         for (int e = 0; e < 4; ++e) {
;           const int off = 32 * s2 + 16 * kk + e;
;           int idx;
;           if (MODE <= 1) { idx = base - 16 * off; idx = idx > 0 ? idx : 0; } else idx = base - off;
;           sv[kk][e] = S[kk][r][e] * (0.125f * LOG2E) + tb[r * TS + idx];
;         }
;       float pv[2][4];
;       if (MODE == 1) {
; #pragma unroll
;         for (int kk = 0; kk < 2; ++kk)
; #pragma unroll
;           for (int e = 0; e < 4; ++e) pv[kk][e] = __builtin_amdgcn_exp2f(sv[kk][e] - m[r]) * inv[r];
; #pragma unroll
;         for (int kk = 0; kk < 2; ++kk) { g1s[kk] += pv[kk][0] + pv[kk][1] + pv[kk][2] + 0.5f * pv[kk][3]; p3s[kk] += 0.5f * pv[kk][3]; }
;       } else {
;         const float mxa = fmaxf(fmaxf(sv[0][0], sv[0][1]), sv[0][2]), mxb = fmaxf(fmaxf(sv[0][3], sv[1][0]), sv[1][1]);
;         float mx = fmaxf(fmaxf(fmaxf(sv[1][2], sv[1][3]), mxa), mxb);
;         if (MODE == 2) mx = selok ? mx : -__builtin_inff();
;         if (__any(mx > m[r] + 8.0f)) {
;           mx = fmaxf(mx, __shfl_xor(mx, 16)); mx = fmaxf(mx, __shfl_xor(mx, 32));
;           const float mn = fmaxf(m[r], mx), al = __builtin_amdgcn_exp2f(m[r] - mn);
;           m[r] = mn; l[r] *= al;
;           if (MODE != 0) {
; #pragma unroll
;             for (int df = 0; df < 4; ++df) O[df][r] *= al;
;           }
;         }
;         const float me = (MODE == 2) ? (selok ? m[r] : __builtin_inff()) : m[r];
;         float ps = 0.f;
; #pragma unroll
;         for (int kk = 0; kk < 2; ++kk)
; #pragma unroll
;           for (int e = 0; e < 4; ++e) { pv[kk][e] = __builtin_amdgcn_exp2f(sv[kk][e] - me); ps += pv[kk][e]; }
;         l[r] += ps;
;       }
;       if (MODE != 0) {
;         const unsigned w0 = pk2(pv[0][0], pv[0][1]), w1 = pk2(pv[0][2], pv[0][3]), w2 = pk2(pv[1][0], pv[1][1]), w3 = pk2(pv[1][2], pv[1][3]);
;         u32x4 pw; pw.x = w0; pw.y = w1; pw.z = w2; pw.w = w3;
;         Pf[r] = __builtin_bit_cast(bf16x8, pw);
;       }
;     }
.LBB0_459:
	v_cndmask_b32_e64 v30, v189, v228, s[36:37]
	v_sub_f32_e32 v31, v47, v30
	v_exp_f32_e32 v31, v31
	v_sub_f32_e32 v46, v46, v30
	v_exp_f32_e32 v46, v46
	v_sub_f32_e32 v113, v113, v30
	v_exp_f32_e32 v113, v113
	v_sub_f32_e32 v112, v112, v30
	v_exp_f32_e32 v112, v112
	v_sub_f32_e32 v45, v45, v30
	v_exp_f32_e32 v45, v45
	v_sub_f32_e32 v44, v44, v30
	v_add_f32_e32 v47, v46, v31
	v_exp_f32_e32 v44, v44
	v_sub_f32_e32 v29, v29, v30
	v_add_f32_e32 v47, v113, v47
	v_exp_f32_e32 v29, v29
	v_sub_f32_e32 v28, v28, v30
	v_add_f32_e32 v47, v112, v47
	v_exp_f32_e32 v28, v28
	v_add_f32_e32 v47, v45, v47
	v_add_f32_e32 v47, v44, v47
	v_add_f32_e32 v47, v29, v47
	s_lshl_b32 s16, s74, 9
	v_add_f32_e32 v30, v28, v47
	v_cvt_pk_bf16_f32 v135, v29, v28
	v_mul_u32_u24_e32 v28, 0x44, v117
	s_add_i32 s73, s72, s16
	v_lshlrev_b32_e32 v28, 1, v28
	v_lshlrev_b32_e32 v29, 1, v118
	v_add3_u32 v28, s73, v28, v29
	v_cvt_pk_bf16_f32 v129, v121, v123
	v_cvt_pk_bf16_f32 v130, v124, v125
	v_add_u32_e32 v123, 0x4000, v28
	v_add_u32_e32 v124, 0x4800, v28
	v_cvt_pk_bf16_f32 v128, v119, v120
	v_cvt_pk_bf16_f32 v131, v126, v127
	v_cvt_pk_bf16_f32 v132, v31, v46
	v_cvt_pk_bf16_f32 v134, v45, v44
	ds_read2_b64 v[44:47], v123 offset1:4
	ds_read2_b64 v[118:121], v124 offset0:16 offset1:20
	v_add_u32_e32 v125, 0x5000, v28
	v_add_u32_e32 v126, 0x5800, v28
	ds_read2_b64 v[136:139], v125 offset0:32 offset1:36
	ds_read2_b64 v[140:143], v126 offset0:48 offset1:52
	v_add_f32_e32 v147, v147, v30
	v_cvt_pk_bf16_f32 v133, v113, v112
	s_setprio 1
	s_waitcnt lgkmcnt(3)
	v_mfma_f32_16x16x32_bf16 v[28:31], v[44:47], v[128:131], v[24:27]
	v_mfma_f32_16x16x32_bf16 v[44:47], v[44:47], v[132:135], v[36:39]
	s_waitcnt lgkmcnt(2)
	v_mfma_f32_16x16x32_bf16 v[24:27], v[118:121], v[128:131], v[16:19]
	v_mfma_f32_16x16x32_bf16 v[40:43], v[118:121], v[132:135], v[40:43]
	s_waitcnt lgkmcnt(1)
	v_mfma_f32_16x16x32_bf16 v[20:23], v[136:139], v[128:131], v[20:23]
	v_mfma_f32_16x16x32_bf16 v[36:39], v[136:139], v[132:135], v[104:107]
	s_waitcnt lgkmcnt(0)
	v_mfma_f32_16x16x32_bf16 v[16:19], v[140:143], v[128:131], v[32:35]
	v_mfma_f32_16x16x32_bf16 v[32:35], v[140:143], v[132:135], v[108:111]
	s_setprio 0
	s_nop 1
	v_add_u32_e32 v108, v115, v114
	v_add_u32_e32 v116, v116, v114
	ds_read_b128 v[104:107], v108 offset:4096
	ds_read_b128 v[108:111], v108 offset:6144
	ds_read_b128 v[112:115], v116 offset:4096
	ds_read_b128 v[116:119], v116 offset:6144
	v_add_u32_e32 v251, 0x8400, v122
	v_add_u32_e32 v250, 0xc500, v122
	ds_read2_b32 v[152:153], v251 offset0:31 offset1:32
	ds_read2_b32 v[154:155], v251 offset0:29 offset1:30
	ds_read2_b32 v[156:157], v251 offset0:15 offset1:16
	ds_read2_b32 v[168:169], v251 offset0:13 offset1:14
	ds_read2_b32 v[170:171], v250 offset0:31 offset1:32
	ds_read2_b32 v[172:173], v250 offset0:29 offset1:30
	ds_read2_b32 v[174:175], v250 offset0:15 offset1:16
	ds_read2_b32 v[192:193], v250 offset0:13 offset1:14
	s_setprio 1
	s_waitcnt lgkmcnt(11)
	v_mfma_f32_16x16x32_bf16 v[128:131], v[104:107], v[0:3], 0
	v_mfma_f32_16x16x32_bf16 v[104:107], v[104:107], v[8:11], 0
	s_waitcnt lgkmcnt(10)
	v_mfma_f32_16x16x32_bf16 v[136:139], v[108:111], v[8:11], 0
	v_mfma_f32_16x16x32_bf16 v[132:135], v[108:111], v[0:3], 0
	s_waitcnt lgkmcnt(9)
	v_mfma_f32_16x16x32_bf16 v[128:131], v[112:115], v[4:7], v[128:131]
	v_mfma_f32_16x16x32_bf16 v[108:111], v[112:115], v[12:15], v[104:107]
	s_waitcnt lgkmcnt(8)
	v_mfma_f32_16x16x32_bf16 v[104:107], v[116:119], v[12:15], v[136:139]
	v_mfma_f32_16x16x32_bf16 v[132:135], v[116:119], v[4:7], v[132:135]
	s_setprio 0
	s_waitcnt lgkmcnt(7)
	s_nop 1
	v_fmamk_f32 v127, v128, 0x3e38aa3b, v153
	v_fmamk_f32 v116, v129, 0x3e38aa3b, v152
	s_waitcnt lgkmcnt(6)
	v_fmamk_f32 v117, v130, 0x3e38aa3b, v155
	v_fmamk_f32 v114, v131, 0x3e38aa3b, v154
	s_waitcnt lgkmcnt(5)
	v_fmamk_f32 v113, v132, 0x3e38aa3b, v157
	v_fmamk_f32 v112, v133, 0x3e38aa3b, v156
	v_max3_f32 v115, v127, v116, v117
	s_waitcnt lgkmcnt(4)
	v_fmamk_f32 v128, v134, 0x3e38aa3b, v169
	v_fmamk_f32 v118, v135, 0x3e38aa3b, v168
	v_max3_f32 v119, v114, v113, v112
	v_max_f32_e32 v120, v128, v118
	v_max3_f32 v115, v120, v115, v119
	v_cndmask_b32_e64 v115, v115, v225, s[36:37]
	v_add_f32_e32 v119, 0x41000000, v188
	v_cmp_gt_f32_e32 vcc, v115, v119
	s_cbranch_vccz .LBB0_461
	ds_bpermute_b32 v119, v233, v115
	v_max_f32_e32 v115, v115, v115
	v_mov_b32_e32 v121, v189
	s_waitcnt lgkmcnt(0)
	v_max_f32_e32 v119, v119, v119
	v_max_f32_e32 v115, v115, v119
	ds_bpermute_b32 v119, v234, v115
	s_waitcnt lgkmcnt(0)
	v_max3_f32 v120, v188, v115, v119
	v_sub_f32_e32 v115, v188, v120
	v_exp_f32_e32 v130, v115
	v_mov_b64_e32 v[188:189], v[120:121]
	v_mul_f32_e32 v146, v146, v130
	v_pk_mul_f32 v[30:31], v[30:31], v[130:131] op_sel_hi:[1,0]
	v_pk_mul_f32 v[28:29], v[28:29], v[130:131] op_sel_hi:[1,0]
	v_pk_mul_f32 v[26:27], v[26:27], v[130:131] op_sel_hi:[1,0]
	v_pk_mul_f32 v[24:25], v[24:25], v[130:131] op_sel_hi:[1,0]
	v_pk_mul_f32 v[22:23], v[22:23], v[130:131] op_sel_hi:[1,0]
	v_pk_mul_f32 v[20:21], v[20:21], v[130:131] op_sel_hi:[1,0]
	v_pk_mul_f32 v[18:19], v[18:19], v[130:131] op_sel_hi:[1,0]
	v_pk_mul_f32 v[16:17], v[16:17], v[130:131] op_sel_hi:[1,0]
	s_branch .LBB0_462

; template <int MODE>
; __device__ __forceinline__ void nsa_compute(int cur, int buf, int t, int hl, u64 mymask, const bf16x8 (&Qf)[2][2], f32x4 (&O)[4][2], float (&m)[2], float (&l)[2],
;                                             const float (&inv)[2], float* impw, char* lds) {
;     ...
;         const float mxa = fmaxf(fmaxf(sv[0][0], sv[0][1]), sv[0][2]), mxb = fmaxf(fmaxf(sv[0][3], sv[1][0]), sv[1][1]);
;         float mx = fmaxf(fmaxf(fmaxf(sv[1][2], sv[1][3]), mxa), mxb);
;         if (MODE == 2) mx = selok ? mx : -__builtin_inff();
;         if (__any(mx > m[r] + 8.0f)) {
;           mx = fmaxf(mx, __shfl_xor(mx, 16)); mx = fmaxf(mx, __shfl_xor(mx, 32));
;           const float mn = fmaxf(m[r], mx), al = __builtin_amdgcn_exp2f(m[r] - mn);
;           m[r] = mn; l[r] *= al;
;           if (MODE != 0) {
; #pragma unroll
;             for (int df = 0; df < 4; ++df) O[df][r] *= al;
;           }
;         }
;         const float me = (MODE == 2) ? (selok ? m[r] : __builtin_inff()) : m[r];
;         float ps = 0.f;
; #pragma unroll
;         for (int kk = 0; kk < 2; ++kk)
; #pragma unroll
;           for (int e = 0; e < 4; ++e) { pv[kk][e] = __builtin_amdgcn_exp2f(sv[kk][e] - me); ps += pv[kk][e]; }
;         l[r] += ps;
.LBB0_473:
	v_cndmask_b32_e64 v136, v188, v228, s[36:37]
	v_sub_f32_e32 v47, v47, v136
	v_exp_f32_e32 v152, v47
	v_sub_f32_e32 v46, v46, v136
	v_exp_f32_e32 v153, v46
	v_sub_f32_e32 v39, v39, v136
	v_exp_f32_e32 v154, v39
	v_sub_f32_e32 v38, v38, v136
	v_exp_f32_e32 v155, v38
	v_sub_f32_e32 v37, v37, v136
	v_add_f32_e32 v47, 0, v152
	v_exp_f32_e32 v156, v37
	v_sub_f32_e32 v36, v36, v136
	v_add_f32_e32 v46, v153, v47
	v_exp_f32_e32 v157, v36
	v_add_f32_e32 v39, v154, v46
	v_add_f32_e32 v38, v155, v39
	v_add_f32_e32 v37, v156, v38
	v_add_f32_e32 v36, v157, v37
	v_sub_f32_e32 v37, v45, v136
	v_exp_f32_e32 v159, v37
	v_sub_f32_e32 v37, v44, v136
	v_exp_f32_e32 v160, v37
	v_add_f32_e32 v36, v159, v36
	v_add_f32_e32 v36, v160, v36
	v_add_f32_e32 v190, v190, v36
	s_waitcnt lgkmcnt(3)
	v_fmamk_f32 v139, v28, 0x3e38aa3b, v203
	v_fmamk_f32 v138, v29, 0x3e38aa3b, v202
	s_waitcnt lgkmcnt(2)
	v_fmamk_f32 v141, v30, 0x3e38aa3b, v205
	v_fmamk_f32 v140, v31, 0x3e38aa3b, v204
	s_waitcnt lgkmcnt(1)
	v_fmamk_f32 v137, v20, 0x3e38aa3b, v207
	v_fmamk_f32 v136, v21, 0x3e38aa3b, v206
	v_max3_f32 v20, v139, v138, v141
	v_max3_f32 v21, v140, v137, v136
	s_waitcnt lgkmcnt(0)
	v_fmamk_f32 v143, v22, 0x3e38aa3b, v209
	v_fmamk_f32 v142, v23, 0x3e38aa3b, v208
	v_max_f32_e32 v22, v143, v142
	v_max3_f32 v20, v22, v20, v21
	v_cndmask_b32_e64 v20, v20, v225, s[36:37]
	v_add_f32_e32 v21, 0x41000000, v189
	v_cmp_gt_f32_e32 vcc, v20, v21
	s_cbranch_vccz .LBB0_475
	ds_bpermute_b32 v21, v233, v20
	v_max_f32_e32 v20, v20, v20
	s_waitcnt lgkmcnt(0)
	v_max_f32_e32 v21, v21, v21
	v_max_f32_e32 v20, v20, v21
	ds_bpermute_b32 v21, v234, v20
	s_waitcnt lgkmcnt(0)
	v_max3_f32 v161, v189, v20, v21
	v_sub_f32_e32 v20, v189, v161
	v_exp_f32_e32 v44, v20
	v_mov_b32_e32 v189, v161
	v_mul_f32_e32 v191, v191, v44
	v_pk_mul_f32 v[22:23], v[110:111], v[44:45] op_sel_hi:[1,0]
	v_pk_mul_f32 v[20:21], v[108:109], v[44:45] op_sel_hi:[1,0]
	v_pk_mul_f32 v[30:31], v[114:115], v[44:45] op_sel_hi:[1,0]
	v_pk_mul_f32 v[28:29], v[112:113], v[44:45] op_sel_hi:[1,0]
	v_pk_mul_f32 v[38:39], v[118:119], v[44:45] op_sel_hi:[1,0]
	v_pk_mul_f32 v[36:37], v[116:117], v[44:45] op_sel_hi:[1,0]
	v_pk_mul_f32 v[46:47], v[122:123], v[44:45] op_sel_hi:[1,0]
	v_pk_mul_f32 v[44:45], v[120:121], v[44:45] op_sel_hi:[1,0]
	s_branch .LBB0_476

; template <int MODE>
; __device__ __forceinline__ void nsa_compute(int cur, int buf, int t, int hl, u64 mymask, const bf16x8 (&Qf)[2][2], f32x4 (&O)[4][2], float (&m)[2], float (&l)[2],
;                                             const float (&inv)[2], float* impw, char* lds) {
;     ...
;     for (int r = 0; r < 2; ++r) {
;       float sv[2][4];
; #pragma unroll
;       for (int kk = 0; kk < 2; ++kk)
; #pragma unroll
;         for (int e = 0; e < 4; ++e) {
;           const int off = 32 * s2 + 16 * kk + e;
;           int idx;
;           if (MODE <= 1) { idx = base - 16 * off; idx = idx > 0 ? idx : 0; } else idx = base - off;
;           sv[kk][e] = S[kk][r][e] * (0.125f * LOG2E) + tb[r * TS + idx];
;         }
;       float pv[2][4];
;       if (MODE == 1) {
; #pragma unroll
;         for (int kk = 0; kk < 2; ++kk)
; #pragma unroll
;           for (int e = 0; e < 4; ++e) pv[kk][e] = __builtin_amdgcn_exp2f(sv[kk][e] - m[r]) * inv[r];
; #pragma unroll
;         for (int kk = 0; kk < 2; ++kk) { g1s[kk] += pv[kk][0] + pv[kk][1] + pv[kk][2] + 0.5f * pv[kk][3]; p3s[kk] += 0.5f * pv[kk][3]; }
;       } else {
;         const float mxa = fmaxf(fmaxf(sv[0][0], sv[0][1]), sv[0][2]), mxb = fmaxf(fmaxf(sv[0][3], sv[1][0]), sv[1][1]);
;         float mx = fmaxf(fmaxf(fmaxf(sv[1][2], sv[1][3]), mxa), mxb);
;         if (MODE == 2) mx = selok ? mx : -__builtin_inff();
;         if (__any(mx > m[r] + 8.0f)) {
;           mx = fmaxf(mx, __shfl_xor(mx, 16)); mx = fmaxf(mx, __shfl_xor(mx, 32));
;           const float mn = fmaxf(m[r], mx), al = __builtin_amdgcn_exp2f(m[r] - mn);
;           m[r] = mn; l[r] *= al;
;           if (MODE != 0) {
; #pragma unroll
;             for (int df = 0; df < 4; ++df) O[df][r] *= al;
;           }
;         }
;         const float me = (MODE == 2) ? (selok ? m[r] : __builtin_inff()) : m[r];
;         float ps = 0.f;
; #pragma unroll
;         for (int kk = 0; kk < 2; ++kk)
; #pragma unroll
;           for (int e = 0; e < 4; ++e) { pv[kk][e] = __builtin_amdgcn_exp2f(sv[kk][e] - me); ps += pv[kk][e]; }
;         l[r] += ps;
;       }
;       if (MODE != 0) {
;         const unsigned w0 = pk2(pv[0][0], pv[0][1]), w1 = pk2(pv[0][2], pv[0][3]), w2 = pk2(pv[1][0], pv[1][1]), w3 = pk2(pv[1][2], pv[1][3]);
;         u32x4 pw; pw.x = w0; pw.y = w1; pw.z = w2; pw.w = w3;
;         Pf[r] = __builtin_bit_cast(bf16x8, pw);
;       }
;     }
.LBB0_476:
	v_cvt_pk_bf16_f32 v152, v152, v153
	v_cvt_pk_bf16_f32 v153, v154, v155
	v_cvt_pk_bf16_f32 v154, v156, v157
	v_cndmask_b32_e64 v156, v189, v228, s[36:37]
	v_sub_f32_e32 v139, v139, v156
	v_exp_f32_e32 v139, v139
	v_sub_f32_e32 v138, v138, v156
	v_exp_f32_e32 v138, v138
	v_sub_f32_e32 v141, v141, v156
	v_exp_f32_e32 v141, v141
	v_sub_f32_e32 v140, v140, v156
	v_exp_f32_e32 v140, v140
	v_sub_f32_e32 v137, v137, v156
	v_cvt_pk_bf16_f32 v155, v159, v160
	v_exp_f32_e32 v159, v137
	v_add_f32_e32 v157, v138, v139
	v_add_f32_e32 v157, v141, v157
	v_add_f32_e32 v157, v140, v157
	v_sub_f32_e32 v136, v136, v156
	v_add_f32_e32 v137, v159, v157
	v_exp_f32_e32 v157, v136
	s_nop 0
	v_add_f32_e32 v136, v157, v137
	v_sub_f32_e32 v137, v143, v156
	v_exp_f32_e32 v143, v137
	v_sub_f32_e32 v137, v142, v156
	v_exp_f32_e32 v142, v137
	v_cvt_pk_bf16_f32 v137, v141, v140
	v_mul_u32_u24_e32 v140, 0x44, v150
	v_add_f32_e32 v136, v143, v136
	v_lshlrev_b32_e32 v140, 1, v140
	v_lshlrev_b32_e32 v141, 1, v151
	v_add_f32_e32 v136, v142, v136
	v_add3_u32 v150, s71, v140, v141
	v_add_f32_e32 v191, v191, v136
	v_cvt_pk_bf16_f32 v136, v139, v138
	v_cvt_pk_bf16_f32 v138, v159, v157
	v_add_u32_e32 v159, 0x4000, v150
	v_add_u32_e32 v160, 0x4800, v150
	v_cvt_pk_bf16_f32 v139, v143, v142
	ds_read2_b64 v[140:143], v159 offset1:4
	ds_read2_b64 v[164:167], v160 offset0:16 offset1:20
	v_add_u32_e32 v161, 0x5000, v150
	v_add_u32_e32 v162, 0x5800, v150
	ds_read2_b64 v[168:171], v161 offset0:32 offset1:36
	ds_read2_b64 v[172:175], v162 offset0:48 offset1:52
	s_setprio 1
	s_waitcnt lgkmcnt(3)
	v_mfma_f32_16x16x32_bf16 v[16:19], v[140:143], v[152:155], v[16:19]
	v_mfma_f32_16x16x32_bf16 v[20:23], v[140:143], v[136:139], v[20:23]
	s_waitcnt lgkmcnt(2)
	v_mfma_f32_16x16x32_bf16 v[24:27], v[164:167], v[152:155], v[24:27]
	v_mfma_f32_16x16x32_bf16 v[28:31], v[164:167], v[136:139], v[28:31]
	s_waitcnt lgkmcnt(1)
	v_mfma_f32_16x16x32_bf16 v[32:35], v[168:171], v[152:155], v[32:35]
	v_mfma_f32_16x16x32_bf16 v[36:39], v[168:171], v[136:139], v[36:39]
	s_waitcnt lgkmcnt(0)
	v_mfma_f32_16x16x32_bf16 v[40:43], v[172:175], v[152:155], v[40:43]
	v_mfma_f32_16x16x32_bf16 v[44:47], v[172:175], v[136:139], v[44:47]
	s_setprio 0
	ds_read_b128 v[136:139], v148 offset:4096
	ds_read_b128 v[140:143], v148 offset:6144
	ds_read_b128 v[150:153], v149 offset:4096
	ds_read_b128 v[154:157], v149 offset:6144
	v_add_u32_e32 v251, 0x8400, v158
	v_add_u32_e32 v250, 0xc500, v158
	ds_read2_b32 v[192:193], v251 offset0:31 offset1:32
	ds_read2_b32 v[194:195], v251 offset0:29 offset1:30
	ds_read2_b32 v[198:199], v251 offset0:15 offset1:16
	ds_read2_b32 v[200:201], v251 offset0:13 offset1:14
	ds_read2_b32 v[202:203], v250 offset0:31 offset1:32
	ds_read2_b32 v[204:205], v250 offset0:29 offset1:30
	ds_read2_b32 v[206:207], v250 offset0:15 offset1:16
	ds_read2_b32 v[208:209], v250 offset0:13 offset1:14
	s_setprio 1
	s_waitcnt lgkmcnt(11)
	v_mfma_f32_16x16x32_bf16 v[164:167], v[136:139], v[0:3], 0
	v_mfma_f32_16x16x32_bf16 v[136:139], v[136:139], v[8:11], 0
	s_waitcnt lgkmcnt(10)
	v_mfma_f32_16x16x32_bf16 v[172:175], v[140:143], v[8:11], 0
	v_mfma_f32_16x16x32_bf16 v[168:171], v[140:143], v[0:3], 0
	s_waitcnt lgkmcnt(9)
	v_mfma_f32_16x16x32_bf16 v[164:167], v[150:153], v[4:7], v[164:167]
	v_mfma_f32_16x16x32_bf16 v[140:143], v[150:153], v[12:15], v[136:139]
	s_waitcnt lgkmcnt(8)
	v_mfma_f32_16x16x32_bf16 v[136:139], v[154:157], v[12:15], v[172:175]
	v_mfma_f32_16x16x32_bf16 v[168:171], v[154:157], v[4:7], v[168:171]
	s_setprio 0
	s_waitcnt lgkmcnt(7)
	s_nop 1
	v_fmamk_f32 v163, v164, 0x3e38aa3b, v193
	v_fmamk_f32 v152, v165, 0x3e38aa3b, v192
	s_waitcnt lgkmcnt(6)
	v_fmamk_f32 v153, v166, 0x3e38aa3b, v195
	v_fmamk_f32 v150, v167, 0x3e38aa3b, v194
	s_waitcnt lgkmcnt(5)
	v_fmamk_f32 v149, v168, 0x3e38aa3b, v199
	v_fmamk_f32 v148, v169, 0x3e38aa3b, v198
	v_max3_f32 v151, v163, v152, v153
	s_waitcnt lgkmcnt(4)
	v_fmamk_f32 v164, v170, 0x3e38aa3b, v201
	v_fmamk_f32 v154, v171, 0x3e38aa3b, v200
	v_max3_f32 v155, v150, v149, v148
	v_max_f32_e32 v156, v164, v154
	v_max3_f32 v151, v156, v151, v155
	v_cndmask_b32_e64 v151, v151, v225, s[36:37]
	v_add_f32_e32 v155, 0x41000000, v188
	v_cmp_gt_f32_e32 vcc, v151, v155
	s_cbranch_vccz .LBB0_478
	ds_bpermute_b32 v155, v233, v151
	v_max_f32_e32 v151, v151, v151
	v_mov_b32_e32 v157, v189
	s_waitcnt lgkmcnt(0)
	v_max_f32_e32 v155, v155, v155
	v_max_f32_e32 v151, v151, v155
	ds_bpermute_b32 v155, v234, v151
	s_waitcnt lgkmcnt(0)
	v_max3_f32 v156, v188, v151, v155
	v_sub_f32_e32 v151, v188, v156
	v_exp_f32_e32 v166, v151
	v_mov_b64_e32 v[188:189], v[156:157]
	v_mul_f32_e32 v190, v190, v166
	v_pk_mul_f32 v[18:19], v[18:19], v[166:167] op_sel_hi:[1,0]
	v_pk_mul_f32 v[16:17], v[16:17], v[166:167] op_sel_hi:[1,0]
	v_pk_mul_f32 v[26:27], v[26:27], v[166:167] op_sel_hi:[1,0]
	v_pk_mul_f32 v[24:25], v[24:25], v[166:167] op_sel_hi:[1,0]
	v_pk_mul_f32 v[34:35], v[34:35], v[166:167] op_sel_hi:[1,0]
	v_pk_mul_f32 v[32:33], v[32:33], v[166:167] op_sel_hi:[1,0]
	v_pk_mul_f32 v[42:43], v[42:43], v[166:167] op_sel_hi:[1,0]
	v_pk_mul_f32 v[40:41], v[40:41], v[166:167] op_sel_hi:[1,0]
	s_branch .LBB0_479
